# NSA_QB table rebalanced: sample slots sum 204, others 304 (sample unit measured ~100 block-units)
# speedup vs baseline: 1.0018x; 1.0018x over previous
_ZL6NSA_QB:
	.byte	109, 48, 47, 0, 110, 65, 25, 4, 80, 69, 45, 10, 90, 67, 44, 3, 108, 52, 43, 1, 91, 66, 42, 5, 105, 56, 41, 2, 97, 57, 36, 14, 111, 74, 11, 8, 107, 73, 18, 6, 101, 77, 17, 9, 84, 75, 29, 16, 102, 55, 35, 12, 104, 59, 34, 7, 98, 58, 33, 13, 106, 51, 32, 15, 127, 76, 63, 39, 122, 85, 60, 37, 125, 96, 53, 31, 121, 83, 81, 19, 117, 88, 79, 20, 126, 87, 70, 21, 124, 86, 72, 22, 120, 82, 64, 38, 119, 89, 71, 24, 112, 92, 54, 46, 123, 93, 61, 27, 116, 94, 68, 26, 115, 99, 62, 28, 118, 114, 49, 23, 113, 100, 50, 40, 103, 95, 78, 30
	.size	_ZL6NSA_QB, 128

	.type	__hip_cuid_aaa9f4bcd633d1df,@object
